# attention chunk 2 prologue: the four norm-bound loads issued together (chunk 1 already did)
# baseline (speedup 1.0000x reference)
.LBB0_202:
	ds_bpermute_b32 v0, v217, v134
	v_mov_b32_e32 v7, v210
	v_readlane_b32 s12, v254, 49
	v_readlane_b32 s13, v254, 50
	s_waitcnt lgkmcnt(0)
	v_add_f32_e32 v0, v134, v0
	ds_bpermute_b32 v2, v218, v0
	v_ashrrev_i32_e32 v129, 31, v128
	v_lshl_add_u64 v[4:5], s[12:13], 0, v[128:129]
	v_readlane_b32 s2, v254, 43
	v_readlane_b32 s3, v254, 44
	s_waitcnt lgkmcnt(0)
	v_add_f32_e32 v0, v0, v2
	ds_bpermute_b32 v2, v217, v135
	v_readlane_b32 s0, v254, 63
	s_lshl_b32 s0, s0, 1
	v_ashrrev_i32_e32 v7, 2, v7
	v_and_b32_e32 v8, -4, v7
	s_waitcnt lgkmcnt(0)
	v_add_f32_e32 v2, v135, v2
	ds_bpermute_b32 v3, v218, v2
	v_ashrrev_i32_e32 v9, 31, v8
	s_mov_b32 s15, s1
	s_sub_i32 s93, 0x7f, s7
	s_lshl_b32 s92, s93, 6
	s_waitcnt lgkmcnt(0)
	v_add_f32_e32 v6, v2, v3
	v_lshlrev_b64 v[2:3], 11, v[4:5]
	v_lshl_add_u64 v[2:3], s[2:3], 0, v[2:3]
	v_readlane_b32 s2, v254, 60
	v_lshl_add_u64 v[2:3], v[2:3], 0, s[0:1]
	v_readlane_b32 s3, v254, 61
	v_readlane_b32 s0, v254, 57
	s_or_b32 s0, s92, s0
	v_lshl_add_u64 v[2:3], s[2:3], 1, v[2:3]
	v_lshl_add_u64 v[2:3], v[8:9], 1, v[2:3]
	v_mov_b64_e32 v[8:9], s[10:11]
	v_mad_u64_u32 v[8:9], s[2:3], v4, s23, v[8:9]
	v_mad_i32_i24 v9, v5, s23, v9
	v_readlane_b32 s2, v254, 47
	v_lshl_add_u64 v[4:5], v[8:9], 0, s[14:15]
	v_readlane_b32 s3, v254, 48
	v_or_b32_e32 v172, s0, v211
	v_ashrrev_i32_e32 v173, 31, v172
	v_lshl_add_u64 v[4:5], s[2:3], 1, v[4:5]
	global_load_ushort v7, v[4:5], off offset:2564
	s_movk_i32 s0, 0x7cf
	s_waitcnt vmcnt(0)
	v_lshlrev_b32_e32 v7, 16, v7
	v_mul_f32_e32 v7, 0xbfb8aa3b, v7
	v_exp_f32_e32 v7, v7
	s_nop 0
	v_add_f32_e32 v7, 1.0, v7
	v_div_scale_f32 v8, s[2:3], v7, v7, 1.0
	v_rcp_f32_e32 v9, v8
	s_nop 0
	v_fma_f32 v10, -v8, v9, 1.0
	v_fmac_f32_e32 v9, v10, v9
	v_div_scale_f32 v10, vcc, 1.0, v7, 1.0
	v_mul_f32_e32 v11, v10, v9
	v_fma_f32 v12, -v8, v11, v10
	v_fmac_f32_e32 v11, v12, v9
	v_fma_f32 v8, -v8, v11, v10
	v_div_fmas_f32 v8, v8, v9, v11
	v_div_fixup_f32 v7, v8, v7, 1.0
	v_div_scale_f32 v8, s[2:3], v0, v0, v7
	v_rcp_f32_e32 v9, v8
	s_nop 0
	v_fma_f32 v10, -v8, v9, 1.0
	v_fmac_f32_e32 v9, v10, v9
	v_div_scale_f32 v10, vcc, v7, v0, v7
	v_mul_f32_e32 v11, v10, v9
	v_fma_f32 v12, -v8, v11, v10
	v_fmac_f32_e32 v11, v12, v9
	v_fma_f32 v8, -v8, v11, v10
	v_div_fmas_f32 v8, v8, v9, v11
	v_div_fixup_f32 v0, v8, v0, v7
	ds_read_b128 v[8:11], v224
	s_waitcnt lgkmcnt(0)
	v_pk_fma_f32 v[10:11], v[86:87], v[0:1], v[10:11] op_sel_hi:[1,0,1]
	v_pk_fma_f32 v[8:9], v[84:85], v[0:1], v[8:9] op_sel_hi:[1,0,1]
	s_nop 0
	v_cvt_pk_bf16_f32 v8, v8, v9
	v_cvt_pk_bf16_f32 v9, v10, v11
	global_store_dwordx2 v[2:3], v[8:9], off
	ds_read_b128 v[8:11], v224 offset:1024
	s_waitcnt lgkmcnt(0)
	v_pk_fma_f32 v[10:11], v[90:91], v[0:1], v[10:11] op_sel_hi:[1,0,1]
	v_pk_fma_f32 v[8:9], v[88:89], v[0:1], v[8:9] op_sel_hi:[1,0,1]
	s_nop 0
	v_cvt_pk_bf16_f32 v8, v8, v9
	v_cvt_pk_bf16_f32 v9, v10, v11
	global_store_dwordx2 v[2:3], v[8:9], off offset:32
	ds_read_b128 v[8:11], v224 offset:2048
	s_waitcnt lgkmcnt(0)
	v_pk_fma_f32 v[10:11], v[94:95], v[0:1], v[10:11] op_sel_hi:[1,0,1]
	v_pk_fma_f32 v[8:9], v[92:93], v[0:1], v[8:9] op_sel_hi:[1,0,1]
	s_nop 0
	v_cvt_pk_bf16_f32 v8, v8, v9
	v_cvt_pk_bf16_f32 v9, v10, v11
	global_store_dwordx2 v[2:3], v[8:9], off offset:64
	ds_read_b128 v[8:11], v224 offset:3072
	s_waitcnt lgkmcnt(0)
	v_pk_fma_f32 v[10:11], v[82:83], v[0:1], v[10:11] op_sel_hi:[1,0,1]
	v_pk_fma_f32 v[8:9], v[80:81], v[0:1], v[8:9] op_sel_hi:[1,0,1]
	s_nop 0
	v_cvt_pk_bf16_f32 v8, v8, v9
	v_cvt_pk_bf16_f32 v9, v10, v11
	global_store_dwordx2 v[2:3], v[8:9], off offset:96
	global_load_ushort v0, v[4:5], off offset:2570
	s_waitcnt vmcnt(0)
	v_lshlrev_b32_e32 v0, 16, v0
	v_mul_f32_e32 v0, 0xbfb8aa3b, v0
	v_exp_f32_e32 v0, v0
	s_nop 0
	v_add_f32_e32 v0, 1.0, v0
	v_div_scale_f32 v4, s[2:3], v0, v0, 1.0
	v_rcp_f32_e32 v5, v4
	s_nop 0
	v_fma_f32 v7, -v4, v5, 1.0
	v_fmac_f32_e32 v5, v7, v5
	v_div_scale_f32 v7, vcc, 1.0, v0, 1.0
	v_mul_f32_e32 v8, v7, v5
	v_fma_f32 v9, -v4, v8, v7
	v_fmac_f32_e32 v8, v9, v5
	v_fma_f32 v4, -v4, v8, v7
	v_div_fmas_f32 v4, v4, v5, v8
	v_div_fixup_f32 v0, v4, v0, 1.0
	v_div_scale_f32 v4, s[2:3], v6, v6, v0
	v_rcp_f32_e32 v5, v4
	v_readlane_b32 s2, v255, 0
	v_readlane_b32 s3, v255, 1
	v_fma_f32 v7, -v4, v5, 1.0
	v_fmac_f32_e32 v5, v7, v5
	v_div_scale_f32 v7, vcc, v0, v6, v0
	v_mul_f32_e32 v8, v7, v5
	v_fma_f32 v9, -v4, v8, v7
	v_fmac_f32_e32 v8, v9, v5
	v_fma_f32 v4, -v4, v8, v7
	v_div_fmas_f32 v4, v4, v5, v8
	v_div_fixup_f32 v0, v4, v6, v0
	ds_read_b128 v[4:7], v224 offset:4096
	s_waitcnt lgkmcnt(0)
	v_pk_fma_f32 v[6:7], v[62:63], v[0:1], v[6:7] op_sel_hi:[1,0,1]
	v_pk_fma_f32 v[4:5], v[60:61], v[0:1], v[4:5] op_sel_hi:[1,0,1]
	s_nop 0
	v_cvt_pk_bf16_f32 v4, v4, v5
	v_cvt_pk_bf16_f32 v5, v6, v7
	global_store_dwordx2 v[2:3], v[4:5], off offset:128
	ds_read_b128 v[4:7], v224 offset:5120
	s_waitcnt lgkmcnt(0)
	v_pk_fma_f32 v[6:7], v[66:67], v[0:1], v[6:7] op_sel_hi:[1,0,1]
	v_pk_fma_f32 v[4:5], v[64:65], v[0:1], v[4:5] op_sel_hi:[1,0,1]
	s_nop 0
	v_cvt_pk_bf16_f32 v4, v4, v5
	v_cvt_pk_bf16_f32 v5, v6, v7
	global_store_dwordx2 v[2:3], v[4:5], off offset:160
	ds_read_b128 v[4:7], v224 offset:6144
	s_waitcnt lgkmcnt(0)
	v_pk_fma_f32 v[6:7], v[38:39], v[0:1], v[6:7] op_sel_hi:[1,0,1]
	v_pk_fma_f32 v[4:5], v[36:37], v[0:1], v[4:5] op_sel_hi:[1,0,1]
	s_nop 0
	v_cvt_pk_bf16_f32 v4, v4, v5
	v_cvt_pk_bf16_f32 v5, v6, v7
	global_store_dwordx2 v[2:3], v[4:5], off offset:192
	ds_read_b128 v[4:7], v224 offset:7168
	s_waitcnt lgkmcnt(0)
	v_pk_fma_f32 v[6:7], v[34:35], v[0:1], v[6:7] op_sel_hi:[1,0,1]
	v_pk_fma_f32 v[4:5], v[32:33], v[0:1], v[4:5] op_sel_hi:[1,0,1]
	s_nop 0
	v_cvt_pk_bf16_f32 v4, v4, v5
	v_cvt_pk_bf16_f32 v5, v6, v7
	global_store_dwordx2 v[2:3], v[4:5], off offset:224
	v_lshl_add_u64 v[2:3], s[12:13], 0, v[172:173]
	v_lshlrev_b64 v[2:3], 10, v[2:3]
	v_lshl_add_u64 v[2:3], v[164:165], 0, v[2:3]
	v_lshl_add_u64 v[2:3], s[2:3], 1, v[2:3]
	s_barrier
	global_load_dwordx4 v[4:7], v[2:3], off
	global_load_dwordx4 v[8:11], v[2:3], off offset:64
	global_load_dwordx4 v[12:15], v[2:3], off offset:128
	global_load_dwordx4 v[16:19], v[2:3], off offset:192
	global_load_dword v0, v[166:167], off
	global_load_dword v43, v[168:169], off
	global_load_dword v44, v[168:169], off offset:256
	global_load_dword v45, v[168:169], off offset:512
	s_mov_b64 s[2:3], 0
	s_waitcnt vmcnt(0)
	v_and_b32_e32 v2, 0x7fffffff, v0
	ds_bpermute_b32 v2, v213, v2
	v_max_f32_e64 v0, |v0|, |v0|
	s_waitcnt lgkmcnt(0)
	v_max_f32_e32 v2, v2, v2
	v_max_f32_e32 v0, v0, v2
	ds_bpermute_b32 v2, v214, v0
	s_waitcnt lgkmcnt(0)
	v_max_f32_e32 v2, v2, v2
	v_max_f32_e32 v0, v0, v2
	ds_bpermute_b32 v2, v215, v0
	s_waitcnt lgkmcnt(0)
	v_max_f32_e32 v2, v2, v2
	v_max_f32_e32 v0, v0, v2
	ds_bpermute_b32 v2, v216, v0
	s_waitcnt lgkmcnt(0)
	v_max_f32_e32 v2, v2, v2
	v_max_f32_e32 v0, v0, v2
	ds_bpermute_b32 v2, v217, v0
	s_waitcnt lgkmcnt(0)
	v_max_f32_e32 v2, v2, v2
	v_max_f32_e32 v20, v0, v2
	v_mov_b32_e32 v0, v43
	ds_bpermute_b32 v21, v218, v20
	s_waitcnt vmcnt(0)
	v_and_b32_e32 v2, 0x7fffffff, v0
	ds_bpermute_b32 v2, v213, v2
	v_max_f32_e64 v0, |v0|, |v0|
	s_waitcnt lgkmcnt(0)
	v_max_f32_e32 v2, v2, v2
	v_max_f32_e32 v0, v0, v2
	ds_bpermute_b32 v2, v214, v0
	s_waitcnt lgkmcnt(0)
	v_max_f32_e32 v2, v2, v2
	v_max_f32_e32 v0, v0, v2
	ds_bpermute_b32 v2, v215, v0
	s_waitcnt lgkmcnt(0)
	v_max_f32_e32 v2, v2, v2
	v_max_f32_e32 v0, v0, v2
	ds_bpermute_b32 v2, v216, v0
	s_waitcnt lgkmcnt(0)
	v_max_f32_e32 v2, v2, v2
	v_max_f32_e32 v0, v0, v2
	ds_bpermute_b32 v2, v217, v0
	s_waitcnt lgkmcnt(0)
	v_max_f32_e32 v2, v2, v2
	v_max_f32_e32 v22, v0, v2
	v_mov_b32_e32 v0, v44
	ds_bpermute_b32 v23, v218, v22
	s_waitcnt vmcnt(0)
	v_and_b32_e32 v2, 0x7fffffff, v0
	ds_bpermute_b32 v2, v213, v2
	v_max_f32_e64 v0, |v0|, |v0|
	s_waitcnt lgkmcnt(0)
	v_max_f32_e32 v2, v2, v2
	v_max_f32_e32 v0, v0, v2
	ds_bpermute_b32 v2, v214, v0
	s_waitcnt lgkmcnt(0)
	v_max_f32_e32 v2, v2, v2
	v_max_f32_e32 v0, v0, v2
	ds_bpermute_b32 v2, v215, v0
	s_waitcnt lgkmcnt(0)
	v_max_f32_e32 v2, v2, v2
	v_max_f32_e32 v0, v0, v2
	ds_bpermute_b32 v2, v216, v0
	s_waitcnt lgkmcnt(0)
	v_max_f32_e32 v2, v2, v2
	v_max_f32_e32 v0, v0, v2
	ds_bpermute_b32 v2, v217, v0
	s_waitcnt lgkmcnt(0)
	v_max_f32_e32 v2, v2, v2
	v_max_f32_e32 v24, v0, v2
	v_mov_b32_e32 v0, v45
	ds_bpermute_b32 v25, v218, v24
	s_waitcnt vmcnt(0)
	v_and_b32_e32 v2, 0x7fffffff, v0
	ds_bpermute_b32 v2, v213, v2
	v_max_f32_e64 v0, |v0|, |v0|
	s_waitcnt lgkmcnt(0)
	v_max_f32_e32 v2, v2, v2
	v_max_f32_e32 v0, v0, v2
	ds_bpermute_b32 v2, v214, v0
	s_waitcnt lgkmcnt(0)
	v_max_f32_e32 v2, v2, v2
	v_max_f32_e32 v0, v0, v2
	ds_bpermute_b32 v2, v215, v0
	s_waitcnt lgkmcnt(0)
	v_max_f32_e32 v2, v2, v2
	v_max_f32_e32 v0, v0, v2
	ds_bpermute_b32 v2, v216, v0
	s_waitcnt lgkmcnt(0)
	v_max_f32_e32 v2, v2, v2
	v_max_f32_e32 v0, v0, v2
	ds_bpermute_b32 v2, v217, v0
	s_waitcnt lgkmcnt(0)
	v_max_f32_e32 v2, v2, v2
	v_max_f32_e32 v173, v0, v2
	ds_bpermute_b32 v225, v218, v173
	v_mov_b32_e32 v0, v221
	v_mov_b32_e32 v2, v220
